# attention KV loop: waves 4-7 run a reordered copy (softmax-finish+PV first, then QK) so the two waves of a SIMD are in complementary MFMA/VALU sections
# baseline (speedup 1.0000x reference)
; #define SBAR() __builtin_amdgcn_sched_barrier(0)
; #define VMW() asm volatile("s_waitcnt vmcnt(0)" ::: "memory")
; #define SLOAD_H(Kp, Vp, k0) do { S.st_v0 = load8(VROW(Vp, k0, sr)); S.st_v1 = load8(VROW(Vp, k0, 32 + sr));              \
;                          S.st_k0 = load8(KROW(Kp, k0)); S.st_k1 = load8(KROW(Kp, k0) + 64); S.st_k2 = load8(KROW(Kp, k0) + 128); } while (0)
; #define SWRITE_HV(bf) do { *(bf16x8*)(V_lds + (bf) * SHM_V + vst0) = S.st_v0; *(bf16x8*)(V_lds + (bf) * SHM_V + vst1) = S.st_v1; } while (0)
; #define SWRITE_H(bf) do { SWRITE_HV(bf); SWRITE_HK(bf); } while (0)
; #define MASKT(P0_, P1_, t) do { const int kb_ = KBASE(t); if (kb_ + KVBLK - 1 > qlo || kb_ <= qlo + QBLK - 1 - W) mask_tile(P0_, P1_, qm - kb_, (unsigned)W); } while (0)
; __device__ __forceinline__ void attn_block(const BlockRef& cur, const BlockRef& nxt, int skv, int W, char* lds, Seam& S) {
;     ...
;     for (int d0 = 0; d0 < NQL_; ++d0) *(bf16x8*)(q_lds + d0 * 1024) = S.qt[d0];
;     SWRITE_HV(0); SBAR();
;     if (NT > 1) { SLOAD_H(Kh, Vh, KBASE(1)); }
;     SBAR(); qkt<0>(pA0, pA1, K_lds, r32, hi, S.qr, q_lds);
;     MASKT(pA0, pA1, 0); partialSM(pA0, pA1, m_reg, mnA, alA);
;     if (NT > 1) { VMW(); SWRITE_H(1); }
;     __syncthreads();
;     ...
;     for (int t = 1; t + 1 < NT; t += 2) {
;         HALF_STEP(pB0, pB1, mnB, alB, pA0, pA1, alA, t, 1, 0, 0);
;         HALF_STEP(pA0, pA1, mnA, alA, pB0, pB1, alB, t + 1, 0, 1, 1);
;     }
.LBB0_531:
	v_max_f32_e32 v33, 0xf149f2ca, v32
	v_cndmask_b32_e64 v172, v33, v199, s[0:1]
	v_mul_f32_e32 v32, 0xbdd53b94, v172
	v_fmamk_f32 v16, v16, 0x3dd53b94, v32
	v_exp_f32_e32 v153, v16
	v_sub_f32_e32 v16, 0xf149f2ca, v33
	v_mul_f32_e32 v16, 0x3dd53b94, v16
	v_exp_f32_e32 v16, v16
	v_fmamk_f32 v17, v17, 0x3dd53b94, v32
	v_fmamk_f32 v18, v18, 0x3dd53b94, v32
	v_fmamk_f32 v19, v19, 0x3dd53b94, v32
	v_cndmask_b32_e64 v216, v16, 1.0, s[0:1]
	s_and_b32 s0, s67, 0x3fffffc0
	s_lshl_b32 s0, s0, 2
	v_fmamk_f32 v20, v20, 0x3dd53b94, v32
	v_fmamk_f32 v21, v21, 0x3dd53b94, v32
	v_fmamk_f32 v22, v22, 0x3dd53b94, v32
	v_fmamk_f32 v23, v23, 0x3dd53b94, v32
	v_fmamk_f32 v24, v24, 0x3dd53b94, v32
	v_fmamk_f32 v25, v25, 0x3dd53b94, v32
	v_fmamk_f32 v26, v26, 0x3dd53b94, v32
	v_fmamk_f32 v27, v27, 0x3dd53b94, v32
	v_fmamk_f32 v28, v28, 0x3dd53b94, v32
	v_fmamk_f32 v29, v29, 0x3dd53b94, v32
	v_fmamk_f32 v30, v30, 0x3dd53b94, v32
	v_fmamk_f32 v31, v31, 0x3dd53b94, v32
	s_waitcnt vmcnt(3)
	v_pk_fma_f32 v[114:115], v[0:1], s[18:19], v[32:33] op_sel_hi:[1,0,0]
	s_add_i32 s0, s0, 0
	v_lshlrev_b32_e32 v1, 4, v201
	v_exp_f32_e32 v155, v17
	v_exp_f32_e32 v127, v18
	v_exp_f32_e32 v154, v19
	v_exp_f32_e32 v126, v20
	v_exp_f32_e32 v152, v21
	v_exp_f32_e32 v124, v22
	v_exp_f32_e32 v125, v23
	v_exp_f32_e32 v120, v24
	v_exp_f32_e32 v123, v25
	v_exp_f32_e32 v118, v26
	v_exp_f32_e32 v121, v27
	v_exp_f32_e32 v116, v28
	v_exp_f32_e32 v122, v29
	v_exp_f32_e32 v117, v30
	v_exp_f32_e32 v119, v31
	v_pk_fma_f32 v[112:113], v[2:3], s[18:19], v[32:33] op_sel_hi:[1,0,0]
	s_add_i32 s0, s0, 0x14000
	v_lshlrev_b32_e32 v0, 3, v201
	v_and_b32_e32 v1, 0xc0, v1
	v_lshlrev_b32_e32 v2, 1, v201
	v_and_or_b32 v1, v0, 24, v1
	v_and_b32_e32 v2, 32, v2
	v_and_b32_e32 v0, 0x100, v0
	s_cmp_lg_u32 0, -1
	v_or3_b32 v0, v1, v2, v0
	s_cselect_b32 s1, 0, 0
	v_pk_fma_f32 v[110:111], v[14:15], s[18:19], v[32:33] op_sel_hi:[1,0,0]
	v_pk_fma_f32 v[108:109], v[12:13], s[18:19], v[32:33] op_sel_hi:[1,0,0]
	s_waitcnt vmcnt(0)
	v_pk_fma_f32 v[106:107], v[10:11], s[18:19], v[32:33] op_sel_hi:[1,0,0]
	v_pk_fma_f32 v[104:105], v[8:9], s[18:19], v[32:33] op_sel_hi:[1,0,0]
	v_pk_fma_f32 v[102:103], v[6:7], s[18:19], v[32:33] op_sel_hi:[1,0,0]
	v_pk_fma_f32 v[100:101], v[4:5], s[18:19], v[32:33] op_sel_hi:[1,0,0]
	v_add_u32_e32 v206, s1, v0
	s_cmp_lt_i32 s66, 3
	v_add_u32_e32 v223, 0xe000, v212
	v_add_u32_e32 v221, 0xe000, v213
	v_add_u32_e32 v222, 0xe000, v215
	v_add_u32_e32 v220, 0xe000, v214
	v_cmp_gt_u32_e64 s[4:5], 32, v201
	v_lshl_add_u32 v205, v210, 2, s0
	v_lshl_add_u32 v204, v202, 2, s0
	s_waitcnt lgkmcnt(0)
	s_barrier
	s_cbranch_scc1 .LBB0_550
	s_add_i32 s0, s35, 0xffffef45
	v_add_u32_e32 v0, s0, v210
	v_mov_b32_e32 v191, v189
	v_sub_u32_e32 v0, v0, v202
	v_mov_b32_e32 v217, 0
	v_lshl_add_u64 v[194:195], s[54:55], 0, v[188:189]
	v_lshl_add_u64 v[196:197], s[48:49], 0, v[190:191]
	s_mov_b32 s54, 2
	v_subrev_u32_e32 v191, s68, v0
	s_add_i32 s55, s68, 0x7f
	v_mov_b32_e32 v48, 0
	v_mov_b32_e32 v49, v217
	v_mov_b32_e32 v50, v217
	v_mov_b32_e32 v51, v217
	v_mov_b32_e32 v52, v217
	v_mov_b32_e32 v53, v217
	v_mov_b32_e32 v54, v217
	v_mov_b32_e32 v55, v217
	v_mov_b32_e32 v56, v217
	v_mov_b32_e32 v57, v217
	v_mov_b32_e32 v58, v217
	v_mov_b32_e32 v59, v217
	v_mov_b32_e32 v60, v217
	v_mov_b32_e32 v61, v217
	v_mov_b32_e32 v62, v217
	v_mov_b32_e32 v63, v217
	v_mov_b32_e32 v32, 0
	v_mov_b32_e32 v33, v217
	v_mov_b32_e32 v34, v217
	v_mov_b32_e32 v35, v217
	v_mov_b32_e32 v36, v217
	v_mov_b32_e32 v37, v217
	v_mov_b32_e32 v38, v217
	v_mov_b32_e32 v39, v217
	v_mov_b32_e32 v40, v217
	v_mov_b32_e32 v41, v217
	v_mov_b32_e32 v42, v217
	v_mov_b32_e32 v43, v217
	v_mov_b32_e32 v44, v217
	v_mov_b32_e32 v45, v217
	v_mov_b32_e32 v46, v217
	v_mov_b32_e32 v47, v217
	v_mov_b32_e32 v16, 0
	v_mov_b32_e32 v17, v217
	v_mov_b32_e32 v18, v217
	v_mov_b32_e32 v19, v217
	v_mov_b32_e32 v20, v217
	v_mov_b32_e32 v21, v217
	v_mov_b32_e32 v22, v217
	v_mov_b32_e32 v23, v217
	v_mov_b32_e32 v24, v217
	v_mov_b32_e32 v25, v217
	v_mov_b32_e32 v26, v217
	v_mov_b32_e32 v27, v217
	v_mov_b32_e32 v28, v217
	v_mov_b32_e32 v29, v217
	v_mov_b32_e32 v30, v217
	v_mov_b32_e32 v31, v217
	v_mov_b32_e32 v0, 0
	v_mov_b32_e32 v1, v217
	v_mov_b32_e32 v2, v217
	v_mov_b32_e32 v3, v217
	v_mov_b32_e32 v4, v217
	v_mov_b32_e32 v5, v217
	v_mov_b32_e32 v6, v217
	v_mov_b32_e32 v7, v217
	v_mov_b32_e32 v8, v217
	v_mov_b32_e32 v9, v217
	v_mov_b32_e32 v10, v217
	v_mov_b32_e32 v11, v217
	v_mov_b32_e32 v12, v217
	v_mov_b32_e32 v13, v217
	v_mov_b32_e32 v14, v217
	v_mov_b32_e32 v15, v217
	v_readfirstlane_b32 s100, v226
	s_nop 0
	s_cmpk_ge_u32 s100, 0x100
	s_cbranch_scc1 .Lg1_b535
	s_branch .LBB0_535

; __device__ __forceinline__ void partialSM(f32x16& p0, f32x16& p1, float& m_reg, float& mn, float& alpha) {
;     ...
;     if (__builtin_expect(__all((pmax - m_reg) * SCALE <= THR), 1)) { mn = m_reg; alpha = 1.f; }
;     else { mn = fmaxf(m_reg, pmax); alpha = __builtin_amdgcn_exp2f((m_reg - mn) * C2); m_reg = mn; }
.LBB0_547:
	s_waitcnt vmcnt(4)
	v_max_f32_e32 v152, v228, v228
	v_max_f32_e32 v152, v152, v172
	v_sub_f32_e32 v153, v228, v152
	v_mul_f32_e32 v153, 0x3dd53b94, v153
	v_exp_f32_e32 v153, v153
	s_waitcnt vmcnt(3)
	v_cndmask_b32_e64 v156, v153, 1.0, s[0:1]
	v_cmp_gt_f32_e32 vcc, 1.0, v156
	s_cbranch_vccz .LBB0_534
	s_and_saveexec_b64 s[48:49], s[4:5]
	s_cbranch_execz .LBB0_533
	ds_write_b32 v205, v156 offset:128
	s_branch .LBB0_533
.Lg1_b533:
	s_or_b64 exec, exec, s[48:49]
	s_waitcnt lgkmcnt(0)
	s_waitcnt vmcnt(2)
	ds_read_b128 v[158:161], v204 offset:224
	s_waitcnt vmcnt(1)
	ds_read_b128 v[162:165], v204 offset:192
	s_waitcnt vmcnt(0)
	ds_read_b128 v[166:169], v204 offset:160
	ds_read_b128 v[170:173], v204 offset:128
	s_waitcnt lgkmcnt(3)
	v_pk_mul_f32 v[62:63], v[62:63], v[160:161]
	s_waitcnt lgkmcnt(2)
	v_pk_mul_f32 v[58:59], v[58:59], v[164:165]
	s_waitcnt lgkmcnt(1)
	v_pk_mul_f32 v[54:55], v[54:55], v[168:169]
	s_waitcnt lgkmcnt(0)
	v_pk_mul_f32 v[50:51], v[50:51], v[172:173]
	v_pk_mul_f32 v[60:61], v[60:61], v[158:159]
	v_pk_mul_f32 v[56:57], v[56:57], v[162:163]
	v_pk_mul_f32 v[52:53], v[52:53], v[166:167]
	v_pk_mul_f32 v[48:49], v[48:49], v[170:171]
	v_pk_mul_f32 v[46:47], v[46:47], v[160:161]
	v_pk_mul_f32 v[42:43], v[42:43], v[164:165]
	v_pk_mul_f32 v[38:39], v[38:39], v[168:169]
	v_pk_mul_f32 v[34:35], v[34:35], v[172:173]
	v_pk_mul_f32 v[44:45], v[44:45], v[158:159]
	v_pk_mul_f32 v[40:41], v[40:41], v[162:163]
	v_pk_mul_f32 v[36:37], v[36:37], v[166:167]
	v_pk_mul_f32 v[32:33], v[32:33], v[170:171]
	v_pk_mul_f32 v[30:31], v[30:31], v[160:161]
	v_pk_mul_f32 v[26:27], v[26:27], v[164:165]
	v_pk_mul_f32 v[22:23], v[22:23], v[168:169]
	v_pk_mul_f32 v[18:19], v[18:19], v[172:173]
	v_pk_mul_f32 v[28:29], v[28:29], v[158:159]
	v_pk_mul_f32 v[24:25], v[24:25], v[162:163]
	v_pk_mul_f32 v[20:21], v[20:21], v[166:167]
	v_pk_mul_f32 v[16:17], v[16:17], v[170:171]
	v_pk_mul_f32 v[14:15], v[14:15], v[160:161]
	v_pk_mul_f32 v[10:11], v[10:11], v[164:165]
	v_pk_mul_f32 v[6:7], v[6:7], v[168:169]
	v_pk_mul_f32 v[2:3], v[2:3], v[172:173]
	v_pk_mul_f32 v[12:13], v[12:13], v[158:159]
	v_pk_mul_f32 v[8:9], v[8:9], v[162:163]
	v_pk_mul_f32 v[4:5], v[4:5], v[166:167]
	v_pk_mul_f32 v[0:1], v[0:1], v[170:171]

; __device__ __forceinline__ void finishSM(f32x16& p0, f32x16& p1, float alpha, float& l_reg, bf16x8& pa0, bf16x8& pa1, bf16x8& pa2, bf16x8& pa3) {
;     for (int r = 0; r < 16; ++r) p1[r] = __builtin_amdgcn_exp2f(p1[r]);
;     float ps = 0; for (int r = 0; r < 16; ++r) ps += p0[r]; for (int r = 0; r < 16; ++r) ps += p1[r];
;     { auto rr = __builtin_amdgcn_permlane32_swap(__float_as_uint(ps), __float_as_uint(ps), false, false);
;       ps = __uint_as_float(rr[0]) + __uint_as_float(rr[1]); }
;     l_reg = l_reg * alpha + ps;
;     ...
;     PK4(p0, 0, pa0); PK4(p0, 8, pa1); PK4(p1, 0, pa2); PK4(p1, 8, pa3);
; template <int VB>
; __device__ __forceinline__ void pv_tile(f32x16* o, int vb0, bf16x8 pa0, bf16x8 pa1, bf16x8 pa2, bf16x8 pa3) {
;     ...
;     PV_D0(0); PV_D0(1); PV_D0(2); PV_D0(3);
.Lg1_b535:
	v_exp_f32_e32 v114, v114
	v_exp_f32_e32 v115, v115
	v_exp_f32_e32 v112, v112
	v_exp_f32_e32 v113, v113
	s_waitcnt vmcnt(1)
	v_exp_f32_e32 v164, v108
	v_exp_f32_e32 v165, v109
	v_exp_f32_e32 v166, v110
	v_exp_f32_e32 v111, v111
	v_add_f32_e32 v64, 0, v153
	v_add_f32_e32 v64, v155, v64
	v_add_f32_e32 v64, v127, v64
	v_add_f32_e32 v64, v154, v64
	v_add_f32_e32 v64, v126, v64
	v_add_f32_e32 v64, v152, v64
	v_add_f32_e32 v64, v124, v64
	v_add_f32_e32 v64, v125, v64
	v_add_f32_e32 v64, v120, v64
	v_add_f32_e32 v64, v123, v64
	v_add_f32_e32 v64, v118, v64
	v_add_f32_e32 v64, v121, v64
	v_add_f32_e32 v64, v116, v64
	v_add_f32_e32 v64, v122, v64
	v_add_f32_e32 v64, v117, v64
	v_add_f32_e32 v64, v119, v64
	v_exp_f32_e32 v156, v100
	v_add_f32_e32 v64, v114, v64
	v_exp_f32_e32 v157, v101
	v_add_f32_e32 v64, v115, v64
	v_exp_f32_e32 v158, v102
	v_add_f32_e32 v64, v112, v64
	v_exp_f32_e32 v159, v103
	v_add_f32_e32 v64, v113, v64
	v_exp_f32_e32 v160, v104
	v_add_f32_e32 v64, v156, v64
	v_exp_f32_e32 v161, v105
	v_add_f32_e32 v64, v157, v64
	v_exp_f32_e32 v162, v106
	v_add_f32_e32 v64, v158, v64
	v_exp_f32_e32 v163, v107
	v_add_f32_e32 v64, v159, v64
	v_add_f32_e32 v64, v160, v64
	v_add_f32_e32 v64, v161, v64
	v_add_f32_e32 v64, v162, v64
	v_add_f32_e32 v64, v163, v64
	v_add_f32_e32 v64, v164, v64
	v_add_f32_e32 v64, v165, v64
	v_add_f32_e32 v64, v166, v64
	v_add_f32_e32 v224, v111, v64
	v_mov_b32_e32 v225, v224
	s_nop 1
	v_permlane32_swap_b32_e32 v224, v225
	v_cvt_pk_bf16_f32 v64, v153, v155
	v_cvt_pk_bf16_f32 v65, v127, v154
	v_cvt_pk_bf16_f32 v66, v126, v152
	v_cvt_pk_bf16_f32 v67, v124, v125
	v_cvt_pk_bf16_f32 v100, v120, v123
	v_cvt_pk_bf16_f32 v101, v118, v121
	v_cvt_pk_bf16_f32 v102, v116, v122
	v_cvt_pk_bf16_f32 v103, v117, v119
	v_cvt_pk_bf16_f32 v104, v114, v115
	v_cvt_pk_bf16_f32 v105, v112, v113
	v_cvt_pk_bf16_f32 v106, v156, v157
	v_cvt_pk_bf16_f32 v107, v158, v159
	v_cvt_pk_bf16_f32 v108, v160, v161
	v_cvt_pk_bf16_f32 v109, v162, v163
	v_cvt_pk_bf16_f32 v110, v164, v165
	v_cvt_pk_bf16_f32 v111, v166, v111
	s_nop 0
	v_permlane32_swap_b32_e32 v64, v66
	v_permlane32_swap_b32_e32 v65, v67
	v_permlane32_swap_b32_e32 v100, v102
	v_permlane32_swap_b32_e32 v101, v103
	v_permlane32_swap_b32_e32 v104, v106
	v_permlane32_swap_b32_e32 v105, v107
	v_permlane32_swap_b32_e32 v108, v110
	v_permlane32_swap_b32_e32 v109, v111
	v_add_u32_e32 v229, s55, v193
	v_add_u32_e32 v112, 1, v229
	v_ashrrev_i32_e32 v113, 31, v112
	v_add_u32_e32 v114, 33, v229
	v_lshlrev_b64 v[112:113], 13, v[112:113]
	v_ashrrev_i32_e32 v115, 31, v114
	v_lshl_add_u64 v[112:113], v[194:195], 0, v[112:113]
	v_lshlrev_b64 v[114:115], 13, v[114:115]
	v_add_u32_e32 v230, s55, v209
	v_lshl_add_u64 v[114:115], v[194:195], 0, v[114:115]
	global_load_dwordx4 v[152:155], v[112:113], off
	global_load_dwordx4 v[156:159], v[114:115], off
	v_add_u32_e32 v112, 1, v230
	v_mad_i64_i32 v[112:113], s[0:1], v112, s9, v[196:197]
	global_load_dwordx4 v[160:163], v[112:113], off
	global_load_dwordx4 v[164:167], v[112:113], off offset:128
	global_load_dwordx4 v[168:171], v[112:113], off offset:256
	ds_read_b64_tr_b16 v[112:113], v206 offset:0
	ds_read_b64_tr_b16 v[114:115], v206 offset:0x800
	ds_read_b64_tr_b16 v[116:117], v206 offset:0x1000
	ds_read_b64_tr_b16 v[118:119], v206 offset:0x1800
	ds_read_b64_tr_b16 v[120:121], v206 offset:0x2000
	ds_read_b64_tr_b16 v[122:123], v206 offset:0x2800
	ds_read_b64_tr_b16 v[124:125], v206 offset:0x3000
	ds_read_b64_tr_b16 v[126:127], v206 offset:0x3800
	s_waitcnt lgkmcnt(0)
	s_nop 0
	v_mfma_f32_32x32x16_bf16 v[48:63], v[64:67], v[112:115], v[48:63]
	ds_read_b64_tr_b16 v[112:113], v206 offset:0x200
	ds_read_b64_tr_b16 v[114:115], v206 offset:0xa00
	v_mfma_f32_32x32x16_bf16 v[48:63], v[100:103], v[116:119], v[48:63]
	ds_read_b64_tr_b16 v[116:117], v206 offset:0x1200
	ds_read_b64_tr_b16 v[118:119], v206 offset:0x1a00
	v_mfma_f32_32x32x16_bf16 v[48:63], v[104:107], v[120:123], v[48:63]
	ds_read_b64_tr_b16 v[120:121], v206 offset:0x2200
	ds_read_b64_tr_b16 v[122:123], v206 offset:0x2a00
	ds_read_b64_tr_b16 v[174:175], v206 offset:0x3200
	ds_read_b64_tr_b16 v[176:177], v206 offset:0x3a00
	s_waitcnt lgkmcnt(0)
	v_mfma_f32_32x32x16_bf16 v[48:63], v[108:111], v[124:127], v[48:63]
	v_mfma_f32_32x32x16_bf16 v[32:47], v[64:67], v[112:115], v[32:47]
	ds_read_b64_tr_b16 v[112:113], v206 offset:0x400
	ds_read_b64_tr_b16 v[114:115], v206 offset:0xc00
	v_mfma_f32_32x32x16_bf16 v[32:47], v[100:103], v[116:119], v[32:47]
	ds_read_b64_tr_b16 v[116:117], v206 offset:0x1400
	ds_read_b64_tr_b16 v[118:119], v206 offset:0x1c00
	v_mfma_f32_32x32x16_bf16 v[32:47], v[104:107], v[120:123], v[32:47]
	ds_read_b64_tr_b16 v[120:121], v206 offset:0x2400
	ds_read_b64_tr_b16 v[122:123], v206 offset:0x2c00
	ds_read_b64_tr_b16 v[124:125], v206 offset:0x3400
	ds_read_b64_tr_b16 v[126:127], v206 offset:0x3c00
	s_waitcnt lgkmcnt(0)
	v_mfma_f32_32x32x16_bf16 v[32:47], v[108:111], v[174:177], v[32:47]
	v_mfma_f32_32x32x16_bf16 v[16:31], v[64:67], v[112:115], v[16:31]
	ds_read_b64_tr_b16 v[112:113], v206 offset:0x600
	ds_read_b64_tr_b16 v[114:115], v206 offset:0xe00
	v_mfma_f32_32x32x16_bf16 v[16:31], v[100:103], v[116:119], v[16:31]
	ds_read_b64_tr_b16 v[116:117], v206 offset:0x1600
	ds_read_b64_tr_b16 v[118:119], v206 offset:0x1e00
	v_mfma_f32_32x32x16_bf16 v[16:31], v[104:107], v[120:123], v[16:31]
	ds_read_b64_tr_b16 v[120:121], v206 offset:0x2600
	ds_read_b64_tr_b16 v[122:123], v206 offset:0x2e00
	ds_read_b64_tr_b16 v[174:175], v206 offset:0x3600
	ds_read_b64_tr_b16 v[176:177], v206 offset:0x3e00
	s_waitcnt lgkmcnt(0)
; template <int KB>
; __device__ __forceinline__ void qkt(f32x16& p0, f32x16& p1, const char* K_lds, int r32, int hi, const bf16x8* qr, const char* q_lds) {
;     p0 = f32x16{}; p1 = f32x16{};
;     const char* kb[4];
; #pragma unroll
;     for (int dd = 0; dd < 4; ++dd) kb[dd] = K_lds + KB * SHM_K + KSWZ(r32, (dd * 16 + hi * 8) * 2);
; #pragma unroll
;     for (int d0 = 0; d0 < 12; ++d0) { const char* a = kb[d0 & 3] + (d0 >> 2) * 128;
;         bf16x8 b0 = *reinterpret_cast<const bf16x8*>(a);
;         bf16x8 b1 = *reinterpret_cast<const bf16x8*>(a + 32 * 384);
;         const bf16x8 qf = d0 < NQR ? qr[d0 < NQR ? d0 : 0] : *reinterpret_cast<const bf16x8*>(q_lds + (d0 - NQR) * 1024);
;         p0 = __builtin_amdgcn_mfma_f32_32x32x16_bf16(b0, qf, p0, 0, 0, 0);
;         p1 = __builtin_amdgcn_mfma_f32_32x32x16_bf16(b1, qf, p1, 0, 0, 0); }
	v_mfma_f32_32x32x16_bf16 v[16:31], v[108:111], v[124:127], v[16:31]
	v_mfma_f32_32x32x16_bf16 v[0:15], v[64:67], v[112:115], v[0:15]
	s_sub_i32 s48, s55, 63
	s_cmp_le_i32 s55, s35
	s_cselect_b64 s[0:1], -1, 0
	s_cmp_gt_i32 s48, s47
	s_cselect_b64 s[48:49], -1, 0
	s_and_b64 s[0:1], s[0:1], s[48:49]
	s_and_b64 vcc, exec, s[0:1]
	v_mfma_f32_32x32x16_bf16 v[0:15], v[100:103], v[116:119], v[0:15]
	v_mfma_f32_32x32x16_bf16 v[0:15], v[104:107], v[120:123], v[0:15]
	v_mfma_f32_32x32x16_bf16 v[0:15], v[108:111], v[174:177], v[0:15]
	ds_read_b128 v[64:67], v212 offset:57344
	ds_read_b128 v[68:71], v223 offset:12288
	s_waitcnt lgkmcnt(1)
	v_mfma_f32_32x32x16_bf16 v[84:99], v[64:67], v[148:151], 0
	ds_read_b128 v[64:67], v213 offset:57344
	ds_read_b128 v[100:103], v221 offset:12288
	s_waitcnt lgkmcnt(2)
	v_mfma_f32_32x32x16_bf16 v[68:83], v[68:71], v[148:151], 0
	s_waitcnt lgkmcnt(1)
	v_mfma_f32_32x32x16_bf16 v[84:99], v[64:67], v[144:147], v[84:99]
	s_waitcnt lgkmcnt(0)
	v_mfma_f32_32x32x16_bf16 v[68:83], v[100:103], v[144:147], v[68:83]
	ds_read_b128 v[64:67], v215 offset:57344
	ds_read_b128 v[100:103], v222 offset:12288
	s_waitcnt lgkmcnt(1)
	v_mfma_f32_32x32x16_bf16 v[84:99], v[64:67], v[140:143], v[84:99]
	s_waitcnt lgkmcnt(0)
	v_mfma_f32_32x32x16_bf16 v[68:83], v[100:103], v[140:143], v[68:83]
	ds_read_b128 v[64:67], v214 offset:57344
	ds_read_b128 v[100:103], v220 offset:12288
	s_waitcnt lgkmcnt(1)
	v_mfma_f32_32x32x16_bf16 v[84:99], v[64:67], v[136:139], v[84:99]
	s_waitcnt lgkmcnt(0)
	v_mfma_f32_32x32x16_bf16 v[68:83], v[100:103], v[136:139], v[68:83]
	ds_read_b128 v[64:67], v212 offset:57472
	ds_read_b128 v[100:103], v223 offset:12416
	s_waitcnt lgkmcnt(1)
	v_mfma_f32_32x32x16_bf16 v[84:99], v[64:67], v[132:135], v[84:99]
	s_waitcnt lgkmcnt(0)
	v_mfma_f32_32x32x16_bf16 v[68:83], v[100:103], v[132:135], v[68:83]
	ds_read_b128 v[64:67], v213 offset:57472
	ds_read_b128 v[100:103], v221 offset:12416
	s_waitcnt lgkmcnt(1)
	v_mfma_f32_32x32x16_bf16 v[84:99], v[64:67], v[128:131], v[84:99]
	s_waitcnt lgkmcnt(0)
	v_mfma_f32_32x32x16_bf16 v[68:83], v[100:103], v[128:131], v[68:83]
	ds_read_b128 v[64:67], v215 offset:57472
	ds_read_b128 v[100:103], v222 offset:12416
	ds_read_b128 v[104:107], v211
	s_waitcnt lgkmcnt(0)
	v_mfma_f32_32x32x16_bf16 v[84:99], v[64:67], v[104:107], v[84:99]
	v_mfma_f32_32x32x16_bf16 v[68:83], v[100:103], v[104:107], v[68:83]
	ds_read_b128 v[64:67], v214 offset:57472
	ds_read_b128 v[100:103], v220 offset:12416
	ds_read_b128 v[104:107], v211 offset:1024
	s_waitcnt lgkmcnt(0)
	v_mfma_f32_32x32x16_bf16 v[84:99], v[64:67], v[104:107], v[84:99]
	v_mfma_f32_32x32x16_bf16 v[68:83], v[100:103], v[104:107], v[68:83]
	ds_read_b128 v[64:67], v212 offset:57600
	ds_read_b128 v[100:103], v223 offset:12544
	ds_read_b128 v[104:107], v211 offset:2048
	s_waitcnt lgkmcnt(0)
	v_mfma_f32_32x32x16_bf16 v[84:99], v[64:67], v[104:107], v[84:99]
	v_mfma_f32_32x32x16_bf16 v[68:83], v[100:103], v[104:107], v[68:83]
	ds_read_b128 v[64:67], v213 offset:57600
	ds_read_b128 v[100:103], v221 offset:12544
	ds_read_b128 v[104:107], v211 offset:3072
	s_waitcnt lgkmcnt(0)
	v_mfma_f32_32x32x16_bf16 v[84:99], v[64:67], v[104:107], v[84:99]
	v_mfma_f32_32x32x16_bf16 v[68:83], v[100:103], v[104:107], v[68:83]
	ds_read_b128 v[64:67], v215 offset:57600
	ds_read_b128 v[100:103], v222 offset:12544
	ds_read_b128 v[104:107], v211 offset:4096
	s_waitcnt lgkmcnt(0)
	v_mfma_f32_32x32x16_bf16 v[84:99], v[64:67], v[104:107], v[84:99]
	v_mfma_f32_32x32x16_bf16 v[68:83], v[100:103], v[104:107], v[68:83]
	ds_read_b128 v[64:67], v214 offset:57600
	ds_read_b128 v[100:103], v220 offset:12544
	ds_read_b128 v[104:107], v211 offset:5120
	s_waitcnt lgkmcnt(0)
	v_mfma_f32_32x32x16_bf16 v[84:99], v[64:67], v[104:107], v[84:99]
	v_mfma_f32_32x32x16_bf16 v[68:83], v[100:103], v[104:107], v[68:83]
	s_nop 15
	s_nop 3
	s_cbranch_vccnz .Lg1_b537
; __device__ __forceinline__ void mask_tile(f32x16& p0, f32x16& p1, int dq, unsigned W) {
;     const float NEG = -__builtin_inff();
; #pragma unroll
;     for (int r = 0; r < 16; ++r) {
;         const int c = (r & 3) + 8 * (r >> 2);
;         if ((unsigned)(dq - c) >= W) p0[r] = NEG;
;         if ((unsigned)(dq - c - 32) >= W) p1[r] = NEG;
;     }
; }
	v_add_u32_e32 v64, 0x107b, v191
	v_cmp_gt_u32_e32 vcc, s33, v64
	v_add_u32_e32 v64, 0x5b, v191
	s_nop 0
	v_cndmask_b32_e32 v84, v198, v84, vcc
	v_cmp_lt_u32_e32 vcc, s56, v64
	v_add_u32_e32 v64, 0x7a, v191
	s_nop 0
	v_cndmask_b32_e32 v68, v198, v68, vcc
	v_cmp_lt_u32_e32 vcc, s56, v64
	v_add_u32_e32 v64, 0x5a, v191
	s_nop 0
	v_cndmask_b32_e32 v85, v198, v85, vcc
	v_cmp_lt_u32_e32 vcc, s56, v64
	v_add_u32_e32 v64, 0x79, v191
	s_nop 0
	v_cndmask_b32_e32 v69, v198, v69, vcc
	v_cmp_lt_u32_e32 vcc, s56, v64
	v_add_u32_e32 v64, 0x59, v191
	s_nop 0
	v_cndmask_b32_e32 v86, v198, v86, vcc
	v_cmp_lt_u32_e32 vcc, s56, v64
	v_add_u32_e32 v64, 0x78, v191
	s_nop 0
	v_cndmask_b32_e32 v70, v198, v70, vcc
	v_cmp_lt_u32_e32 vcc, s56, v64
	v_add_u32_e32 v64, 0x58, v191
	s_nop 0
	v_cndmask_b32_e32 v87, v198, v87, vcc
	v_cmp_lt_u32_e32 vcc, s56, v64
	v_add_u32_e32 v64, 0x73, v191
	s_nop 0
	v_cndmask_b32_e32 v71, v198, v71, vcc
	v_cmp_lt_u32_e32 vcc, s56, v64
	v_add_u32_e32 v64, 0x53, v191
	s_nop 0
	v_cndmask_b32_e32 v88, v198, v88, vcc
	v_cmp_lt_u32_e32 vcc, s56, v64
	v_add_u32_e32 v64, 0x72, v191
	s_nop 0
	v_cndmask_b32_e32 v72, v198, v72, vcc
	v_cmp_lt_u32_e32 vcc, s56, v64
	v_add_u32_e32 v64, 0x52, v191
	s_nop 0
	v_cndmask_b32_e32 v89, v198, v89, vcc
	v_cmp_lt_u32_e32 vcc, s56, v64
	v_add_u32_e32 v64, 0x71, v191
	s_nop 0
	v_cndmask_b32_e32 v73, v198, v73, vcc
	v_cmp_lt_u32_e32 vcc, s56, v64
	v_add_u32_e32 v64, 0x51, v191
	s_nop 0
	v_cndmask_b32_e32 v90, v198, v90, vcc
	v_cmp_lt_u32_e32 vcc, s56, v64
	v_add_u32_e32 v64, 0x70, v191
	s_nop 0
	v_cndmask_b32_e32 v74, v198, v74, vcc
	v_cmp_lt_u32_e32 vcc, s56, v64
	v_add_u32_e32 v64, 0x50, v191
	s_nop 0
	v_cndmask_b32_e32 v91, v198, v91, vcc
	v_cmp_lt_u32_e32 vcc, s56, v64
	v_add_u32_e32 v64, 0x6b, v191
	s_nop 0
	v_cndmask_b32_e32 v75, v198, v75, vcc
	v_cmp_lt_u32_e32 vcc, s56, v64
	v_add_u32_e32 v64, 0x4b, v191
	s_nop 0
	v_cndmask_b32_e32 v92, v198, v92, vcc
	v_cmp_lt_u32_e32 vcc, s56, v64
	v_add_u32_e32 v64, 0x6a, v191
	s_nop 0
	v_cndmask_b32_e32 v76, v198, v76, vcc
	v_cmp_lt_u32_e32 vcc, s56, v64
	v_add_u32_e32 v64, 0x4a, v191
	s_nop 0
	v_cndmask_b32_e32 v93, v198, v93, vcc
	v_cmp_lt_u32_e32 vcc, s56, v64
	v_add_u32_e32 v64, 0x69, v191
	s_nop 0
	v_cndmask_b32_e32 v77, v198, v77, vcc
	v_cmp_lt_u32_e32 vcc, s56, v64
	v_add_u32_e32 v64, 0x49, v191
	s_nop 0
	v_cndmask_b32_e32 v94, v198, v94, vcc
	v_cmp_lt_u32_e32 vcc, s56, v64
	v_add_u32_e32 v64, 0x68, v191
	s_nop 0
	v_cndmask_b32_e32 v78, v198, v78, vcc
	v_cmp_lt_u32_e32 vcc, s56, v64
	v_add_u32_e32 v64, 0x48, v191
	s_nop 0
	v_cndmask_b32_e32 v95, v198, v95, vcc
	v_cmp_lt_u32_e32 vcc, s56, v64
	v_add_u32_e32 v64, 0x63, v191
	s_nop 0
	v_cndmask_b32_e32 v79, v198, v79, vcc
	v_cmp_lt_u32_e32 vcc, s56, v64
	v_add_u32_e32 v64, 0x43, v191
	s_nop 0
	v_cndmask_b32_e32 v96, v198, v96, vcc
	v_cmp_lt_u32_e32 vcc, s56, v64
	v_add_u32_e32 v64, 0x62, v191
	s_nop 0
	v_cndmask_b32_e32 v80, v198, v80, vcc
	v_cmp_lt_u32_e32 vcc, s56, v64
	v_add_u32_e32 v64, 0x42, v191
	s_nop 0
	v_cndmask_b32_e32 v97, v198, v97, vcc
	v_cmp_lt_u32_e32 vcc, s56, v64
	v_add_u32_e32 v64, 0x61, v191
	s_nop 0
	v_cndmask_b32_e32 v81, v198, v81, vcc
	v_cmp_lt_u32_e32 vcc, s56, v64
	v_add_u32_e32 v64, 0x41, v191
	s_nop 0
	v_cndmask_b32_e32 v98, v198, v98, vcc
	v_cmp_lt_u32_e32 vcc, s56, v64
	v_add_u32_e32 v64, 0x60, v191
	s_nop 0
	v_cndmask_b32_e32 v82, v198, v82, vcc
	v_cmp_lt_u32_e32 vcc, s56, v64
	v_add_u32_e32 v64, 64, v191
	s_nop 0
	v_cndmask_b32_e32 v99, v198, v99, vcc
	v_cmp_lt_u32_e32 vcc, s56, v64
	s_nop 1
	v_cndmask_b32_e32 v83, v198, v83, vcc

; __device__ __forceinline__ void partialSM(f32x16& p0, f32x16& p1, float& m_reg, float& mn, float& alpha) {
;     ...
;     const float mnL = -mn * C2;
;     for (int r = 0; r < 16; ++r) p0[r] = fmaf(p0[r], C2, mnL); for (int r = 0; r < 16; ++r) p1[r] = fmaf(p1[r], C2, mnL);
;     for (int r = 0; r < 16; ++r) p0[r] = __builtin_amdgcn_exp2f(p0[r]);
; }
; __device__ __forceinline__ void finishSM(f32x16& p0, f32x16& p1, float alpha, float& l_reg, bf16x8& pa0, bf16x8& pa1, bf16x8& pa2, bf16x8& pa3) {
;     for (int r = 0; r < 16; ++r) p1[r] = __builtin_amdgcn_exp2f(p1[r]);
;     float ps = 0; for (int r = 0; r < 16; ++r) ps += p0[r]; for (int r = 0; r < 16; ++r) ps += p1[r];
;     { auto rr = __builtin_amdgcn_permlane32_swap(__float_as_uint(ps), __float_as_uint(ps), false, false);
;       ps = __uint_as_float(rr[0]) + __uint_as_float(rr[1]); }
;     l_reg = l_reg * alpha + ps;
;     ...
;     PK4(p0, 0, pa0); PK4(p0, 8, pa1); PK4(p1, 0, pa2); PK4(p1, 8, pa3);
.Lg1_b541:
	v_cndmask_b32_e64 v228, v64, v172, s[0:1]
	v_mul_f32_e32 v172, 0xbdd53b94, v228
	v_fmamk_f32 v64, v84, 0x3dd53b94, v172
	v_fmamk_f32 v65, v85, 0x3dd53b94, v172
	v_fmamk_f32 v66, v86, 0x3dd53b94, v172
	v_fmamk_f32 v67, v87, 0x3dd53b94, v172
	v_fmamk_f32 v100, v88, 0x3dd53b94, v172
	v_fmamk_f32 v101, v89, 0x3dd53b94, v172
	v_fmamk_f32 v102, v90, 0x3dd53b94, v172
	v_fmamk_f32 v103, v91, 0x3dd53b94, v172
	v_fmamk_f32 v104, v92, 0x3dd53b94, v172
	v_fmamk_f32 v105, v93, 0x3dd53b94, v172
	v_fmamk_f32 v106, v94, 0x3dd53b94, v172
	v_fmamk_f32 v107, v95, 0x3dd53b94, v172
	v_fmamk_f32 v96, v96, 0x3dd53b94, v172
	v_fmamk_f32 v97, v97, 0x3dd53b94, v172
	v_fmamk_f32 v98, v98, 0x3dd53b94, v172
	v_fmamk_f32 v99, v99, 0x3dd53b94, v172
	v_fmamk_f32 v84, v68, 0x3dd53b94, v172
	v_fmamk_f32 v93, v69, 0x3dd53b94, v172
	v_fmamk_f32 v94, v70, 0x3dd53b94, v172
	v_fmamk_f32 v95, v71, 0x3dd53b94, v172
	v_fmamk_f32 v173, v72, 0x3dd53b94, v172
	v_fmamk_f32 v85, v73, 0x3dd53b94, v172
	v_fmamk_f32 v86, v74, 0x3dd53b94, v172
	v_fmamk_f32 v87, v75, 0x3dd53b94, v172
	v_fmamk_f32 v88, v76, 0x3dd53b94, v172
	v_fmamk_f32 v89, v77, 0x3dd53b94, v172
	v_fmamk_f32 v90, v78, 0x3dd53b94, v172
	v_fmamk_f32 v91, v79, 0x3dd53b94, v172
	v_exp_f32_e32 v64, v64
	v_exp_f32_e32 v65, v65
	v_exp_f32_e32 v66, v66
	v_exp_f32_e32 v67, v67
	v_exp_f32_e32 v68, v100
	v_exp_f32_e32 v69, v101
	v_exp_f32_e32 v70, v102
	v_exp_f32_e32 v71, v103
	v_exp_f32_e32 v72, v104
	v_exp_f32_e32 v73, v105
	v_exp_f32_e32 v74, v106
	v_exp_f32_e32 v75, v107
	v_exp_f32_e32 v76, v96
	v_exp_f32_e32 v77, v97
	v_exp_f32_e32 v78, v98
	v_exp_f32_e32 v79, v99
	v_fmamk_f32 v92, v80, 0x3dd53b94, v172
	v_fmamk_f32 v174, v81, 0x3dd53b94, v172
	v_fmamk_f32 v175, v82, 0x3dd53b94, v172
	v_fmac_f32_e32 v172, 0x3dd53b94, v83
	s_waitcnt lgkmcnt(0)
	s_barrier
	ds_write_b128 v218, v[152:155]
	ds_write_b128 v219, v[156:159]
	v_exp_f32_e32 v85, v85
	v_exp_f32_e32 v86, v86
	v_exp_f32_e32 v87, v87
	v_exp_f32_e32 v88, v88
	v_exp_f32_e32 v89, v89
	v_exp_f32_e32 v90, v90
	v_exp_f32_e32 v91, v91
	v_exp_f32_e32 v92, v92
	v_exp_f32_e32 v83, v95
	v_exp_f32_e32 v95, v172
	v_add_f32_e32 v172, 0, v64
	v_add_f32_e32 v172, v65, v172
	v_add_f32_e32 v172, v66, v172
	v_add_f32_e32 v172, v67, v172
	v_add_f32_e32 v172, v68, v172
	v_add_f32_e32 v172, v69, v172
	v_add_f32_e32 v172, v70, v172
	v_add_f32_e32 v172, v71, v172
	v_add_f32_e32 v172, v72, v172
	v_add_f32_e32 v172, v73, v172
	v_add_f32_e32 v172, v74, v172
	v_add_f32_e32 v172, v75, v172
	v_exp_f32_e32 v80, v84
	v_add_f32_e32 v172, v76, v172
	v_exp_f32_e32 v81, v93
	v_add_f32_e32 v172, v77, v172
	v_exp_f32_e32 v82, v94
	v_add_f32_e32 v172, v78, v172
	v_add_f32_e32 v172, v79, v172
	v_exp_f32_e32 v84, v173
	v_add_f32_e32 v172, v80, v172
	v_add_f32_e32 v172, v81, v172
	v_add_f32_e32 v172, v82, v172
	v_add_f32_e32 v172, v83, v172
	v_add_f32_e32 v172, v84, v172
	v_add_f32_e32 v172, v85, v172
	v_add_f32_e32 v172, v86, v172
	v_add_f32_e32 v172, v87, v172
	v_add_f32_e32 v172, v88, v172
	v_exp_f32_e32 v93, v174
	v_add_f32_e32 v172, v89, v172
	v_exp_f32_e32 v94, v175
	v_add_f32_e32 v172, v90, v172
	v_add_f32_e32 v172, v91, v172
	v_add_f32_e32 v172, v92, v172
	v_add_f32_e32 v172, v93, v172
	v_add_f32_e32 v172, v94, v172
	v_add_f32_e32 v231, v95, v172
	v_mov_b32_e32 v232, v231
	v_cvt_pk_bf16_f32 v172, v64, v65
	v_cvt_pk_bf16_f32 v173, v66, v67
	v_cvt_pk_bf16_f32 v174, v68, v69
	v_cvt_pk_bf16_f32 v175, v70, v71
	v_cvt_pk_bf16_f32 v176, v72, v73
	v_cvt_pk_bf16_f32 v177, v74, v75
	v_cvt_pk_bf16_f32 v178, v76, v77
	v_cvt_pk_bf16_f32 v179, v78, v79
	v_cvt_pk_bf16_f32 v180, v80, v81
	v_cvt_pk_bf16_f32 v181, v82, v83
	v_cvt_pk_bf16_f32 v182, v84, v85
	v_cvt_pk_bf16_f32 v183, v86, v87
	v_cvt_pk_bf16_f32 v184, v88, v89
	v_cvt_pk_bf16_f32 v185, v90, v91
	v_cvt_pk_bf16_f32 v186, v92, v93
	v_cvt_pk_bf16_f32 v187, v94, v95
	s_nop 1
	v_permlane32_swap_b32_e32 v231, v232
	v_permlane32_swap_b32_e32 v172, v174
	v_permlane32_swap_b32_e32 v173, v175
	v_permlane32_swap_b32_e32 v176, v178
	v_permlane32_swap_b32_e32 v177, v179
	v_permlane32_swap_b32_e32 v180, v182
	v_permlane32_swap_b32_e32 v181, v183
	v_permlane32_swap_b32_e32 v184, v186
	v_permlane32_swap_b32_e32 v185, v187
	s_add_i32 s0, s54, 1
	s_cmp_lt_i32 s0, s66
	s_cselect_b64 s[48:49], -1, 0
	s_cmp_ge_i32 s0, s66
	s_cbranch_scc1 .Lg1_b543
	v_add_u32_e32 v152, 0x41, v229
	v_add_u32_e32 v154, 0x61, v229
	v_ashrrev_i32_e32 v153, 31, v152
	v_ashrrev_i32_e32 v155, 31, v154
	v_lshlrev_b64 v[152:153], 13, v[152:153]
	v_lshlrev_b64 v[154:155], 13, v[154:155]
	v_add_u32_e32 v160, 0x41, v230
	v_lshl_add_u64 v[152:153], v[194:195], 0, v[152:153]
	v_lshl_add_u64 v[156:157], v[194:195], 0, v[154:155]
	v_mad_i64_i32 v[168:169], s[0:1], v160, s9, v[196:197]
	global_load_dwordx4 v[152:155], v[152:153], off
	s_nop 0
	global_load_dwordx4 v[156:159], v[156:157], off
	s_nop 0
	global_load_dwordx4 v[160:163], v[168:169], off
	global_load_dwordx4 v[164:167], v[168:169], off offset:128
	s_nop 0
	global_load_dwordx4 v[168:171], v[168:169], off offset:256
; template <int KB>
; __device__ __forceinline__ void qkt(f32x16& p0, f32x16& p1, const char* K_lds, int r32, int hi, const bf16x8* qr, const char* q_lds) {
;     p0 = f32x16{}; p1 = f32x16{};
;     const char* kb[4];
; #pragma unroll
;     for (int dd = 0; dd < 4; ++dd) kb[dd] = K_lds + KB * SHM_K + KSWZ(r32, (dd * 16 + hi * 8) * 2);
; #pragma unroll
;     for (int d0 = 0; d0 < 12; ++d0) { const char* a = kb[d0 & 3] + (d0 >> 2) * 128;
;         bf16x8 b0 = *reinterpret_cast<const bf16x8*>(a);
;         bf16x8 b1 = *reinterpret_cast<const bf16x8*>(a + 32 * 384);
;         const bf16x8 qf = d0 < NQR ? qr[d0 < NQR ? d0 : 0] : *reinterpret_cast<const bf16x8*>(q_lds + (d0 - NQR) * 1024);
;         p0 = __builtin_amdgcn_mfma_f32_32x32x16_bf16(b0, qf, p0, 0, 0, 0);
;         p1 = __builtin_amdgcn_mfma_f32_32x32x16_bf16(b1, qf, p1, 0, 0, 0); }
; template <int VB>
; __device__ __forceinline__ void pv_tile(f32x16* o, int vb0, bf16x8 pa0, bf16x8 pa1, bf16x8 pa2, bf16x8 pa3) {
;     ...
;     PV_D0(0); PV_D0(1); PV_D0(2); PV_D0(3);
.Lg1_b543:
	ds_read_b64_tr_b16 v[234:235], v206 offset:0x4000
	ds_read_b64_tr_b16 v[236:237], v206 offset:0x4800
	ds_read_b64_tr_b16 v[238:239], v206 offset:0x5000
	ds_read_b64_tr_b16 v[240:241], v206 offset:0x5800
	ds_read_b64_tr_b16 v[242:243], v206 offset:0x6000
	ds_read_b64_tr_b16 v[244:245], v206 offset:0x6800
	ds_read_b64_tr_b16 v[246:247], v206 offset:0x7000
	ds_read_b64_tr_b16 v[248:249], v206 offset:0x7800
	s_waitcnt lgkmcnt(0)
	s_add_i32 s67, s55, 1
	v_mfma_f32_32x32x16_bf16 v[48:63], v[172:175], v[234:237], v[48:63]
	ds_read_b64_tr_b16 v[234:235], v206 offset:0x4200
	ds_read_b64_tr_b16 v[236:237], v206 offset:0x4a00
	v_mfma_f32_32x32x16_bf16 v[48:63], v[176:179], v[238:241], v[48:63]
	ds_read_b64_tr_b16 v[238:239], v206 offset:0x5200
	ds_read_b64_tr_b16 v[240:241], v206 offset:0x5a00
	v_mfma_f32_32x32x16_bf16 v[48:63], v[180:183], v[242:245], v[48:63]
	ds_read_b64_tr_b16 v[242:243], v206 offset:0x6200
	ds_read_b64_tr_b16 v[244:245], v206 offset:0x6a00
	ds_read_b64_tr_b16 v[250:251], v206 offset:0x7200
	ds_read_b64_tr_b16 v[252:253], v206 offset:0x7a00
	s_waitcnt lgkmcnt(0)
	v_mfma_f32_32x32x16_bf16 v[48:63], v[184:187], v[246:249], v[48:63]
	v_mfma_f32_32x32x16_bf16 v[32:47], v[172:175], v[234:237], v[32:47]
	ds_read_b64_tr_b16 v[234:235], v206 offset:0x4400
	ds_read_b64_tr_b16 v[236:237], v206 offset:0x4c00
	v_mfma_f32_32x32x16_bf16 v[32:47], v[176:179], v[238:241], v[32:47]
	ds_read_b64_tr_b16 v[238:239], v206 offset:0x5400
	ds_read_b64_tr_b16 v[240:241], v206 offset:0x5c00
	v_mfma_f32_32x32x16_bf16 v[32:47], v[180:183], v[242:245], v[32:47]
	ds_read_b64_tr_b16 v[242:243], v206 offset:0x6400
	ds_read_b64_tr_b16 v[244:245], v206 offset:0x6c00
	ds_read_b64_tr_b16 v[246:247], v206 offset:0x7400
	ds_read_b64_tr_b16 v[248:249], v206 offset:0x7c00
	s_waitcnt lgkmcnt(0)
	v_mfma_f32_32x32x16_bf16 v[32:47], v[184:187], v[250:253], v[32:47]
	v_mfma_f32_32x32x16_bf16 v[16:31], v[172:175], v[234:237], v[16:31]
	ds_read_b64_tr_b16 v[234:235], v206 offset:0x4600
	ds_read_b64_tr_b16 v[236:237], v206 offset:0x4e00
	v_mfma_f32_32x32x16_bf16 v[16:31], v[176:179], v[238:241], v[16:31]
	ds_read_b64_tr_b16 v[238:239], v206 offset:0x5600
	ds_read_b64_tr_b16 v[240:241], v206 offset:0x5e00
	v_mfma_f32_32x32x16_bf16 v[16:31], v[180:183], v[242:245], v[16:31]
	ds_read_b64_tr_b16 v[242:243], v206 offset:0x6600
	ds_read_b64_tr_b16 v[244:245], v206 offset:0x6e00
	ds_read_b64_tr_b16 v[250:251], v206 offset:0x7600
	ds_read_b64_tr_b16 v[252:253], v206 offset:0x7e00
	s_waitcnt lgkmcnt(0)
	v_mfma_f32_32x32x16_bf16 v[16:31], v[184:187], v[246:249], v[16:31]
	v_mfma_f32_32x32x16_bf16 v[0:15], v[172:175], v[234:237], v[0:15]
	s_add_i32 s0, s55, 64
	s_cmp_le_i32 s0, s35
	s_cselect_b64 s[0:1], -1, 0
	s_cmp_gt_i32 s67, s47
	s_cselect_b64 s[68:69], -1, 0
	s_and_b64 s[0:1], s[0:1], s[68:69]
	s_and_b64 vcc, exec, s[0:1]
	v_mfma_f32_32x32x16_bf16 v[0:15], v[176:179], v[238:241], v[0:15]
	v_mfma_f32_32x32x16_bf16 v[0:15], v[180:183], v[242:245], v[0:15]
	v_mfma_f32_32x32x16_bf16 v[0:15], v[184:187], v[250:253], v[0:15]
	ds_read_b128 v[80:83], v212 offset:32768
	ds_read_b128 v[96:99], v212 offset:45056
	s_waitcnt lgkmcnt(1)
	v_mfma_f32_32x32x16_bf16 v[112:127], v[80:83], v[148:151], 0
	ds_read_b128 v[80:83], v213 offset:32768
	ds_read_b128 v[176:179], v213 offset:45056
	s_waitcnt lgkmcnt(2)
	v_mfma_f32_32x32x16_bf16 v[96:111], v[96:99], v[148:151], 0
	s_waitcnt lgkmcnt(1)
	v_mfma_f32_32x32x16_bf16 v[112:127], v[80:83], v[144:147], v[112:127]
	s_waitcnt lgkmcnt(0)
	v_mfma_f32_32x32x16_bf16 v[96:111], v[176:179], v[144:147], v[96:111]
	ds_read_b128 v[80:83], v215 offset:32768
	ds_read_b128 v[176:179], v215 offset:45056
	s_waitcnt lgkmcnt(1)
	v_mfma_f32_32x32x16_bf16 v[112:127], v[80:83], v[140:143], v[112:127]
	s_waitcnt lgkmcnt(0)
	v_mfma_f32_32x32x16_bf16 v[96:111], v[176:179], v[140:143], v[96:111]
	ds_read_b128 v[80:83], v214 offset:32768
	ds_read_b128 v[176:179], v214 offset:45056
	s_waitcnt lgkmcnt(1)
	v_mfma_f32_32x32x16_bf16 v[112:127], v[80:83], v[136:139], v[112:127]
	s_waitcnt lgkmcnt(0)
	v_mfma_f32_32x32x16_bf16 v[96:111], v[176:179], v[136:139], v[96:111]
	ds_read_b128 v[80:83], v212 offset:32896
	ds_read_b128 v[176:179], v212 offset:45184
	s_waitcnt lgkmcnt(1)
	v_mfma_f32_32x32x16_bf16 v[112:127], v[80:83], v[132:135], v[112:127]
	s_waitcnt lgkmcnt(0)
	v_mfma_f32_32x32x16_bf16 v[96:111], v[176:179], v[132:135], v[96:111]
	ds_read_b128 v[80:83], v213 offset:32896
	ds_read_b128 v[176:179], v213 offset:45184
	s_waitcnt lgkmcnt(1)
	v_mfma_f32_32x32x16_bf16 v[112:127], v[80:83], v[128:131], v[112:127]
	s_waitcnt lgkmcnt(0)
	v_mfma_f32_32x32x16_bf16 v[96:111], v[176:179], v[128:131], v[96:111]
	ds_read_b128 v[80:83], v215 offset:32896
	ds_read_b128 v[176:179], v215 offset:45184
	ds_read_b128 v[180:183], v211
	s_waitcnt lgkmcnt(0)
	v_mfma_f32_32x32x16_bf16 v[112:127], v[80:83], v[180:183], v[112:127]
	v_mfma_f32_32x32x16_bf16 v[96:111], v[176:179], v[180:183], v[96:111]
	ds_read_b128 v[80:83], v214 offset:32896
	ds_read_b128 v[176:179], v214 offset:45184
	ds_read_b128 v[180:183], v211 offset:1024
	s_waitcnt lgkmcnt(0)
	v_mfma_f32_32x32x16_bf16 v[112:127], v[80:83], v[180:183], v[112:127]
	v_mfma_f32_32x32x16_bf16 v[96:111], v[176:179], v[180:183], v[96:111]
	ds_read_b128 v[80:83], v212 offset:33024
	ds_read_b128 v[176:179], v212 offset:45312
	ds_read_b128 v[180:183], v211 offset:2048
	s_waitcnt lgkmcnt(0)
	v_mfma_f32_32x32x16_bf16 v[112:127], v[80:83], v[180:183], v[112:127]
	v_mfma_f32_32x32x16_bf16 v[96:111], v[176:179], v[180:183], v[96:111]
	ds_read_b128 v[80:83], v213 offset:33024
	ds_read_b128 v[176:179], v213 offset:45312
	ds_read_b128 v[180:183], v211 offset:3072
	s_waitcnt lgkmcnt(0)
	v_mfma_f32_32x32x16_bf16 v[112:127], v[80:83], v[180:183], v[112:127]
	v_mfma_f32_32x32x16_bf16 v[96:111], v[176:179], v[180:183], v[96:111]
	ds_read_b128 v[80:83], v215 offset:33024
	ds_read_b128 v[176:179], v215 offset:45312
	ds_read_b128 v[180:183], v211 offset:4096
	s_waitcnt lgkmcnt(0)
	v_mfma_f32_32x32x16_bf16 v[112:127], v[80:83], v[180:183], v[112:127]
	v_mfma_f32_32x32x16_bf16 v[96:111], v[176:179], v[180:183], v[96:111]
	ds_read_b128 v[80:83], v214 offset:33024
	ds_read_b128 v[176:179], v214 offset:45312
	ds_read_b128 v[180:183], v211 offset:5120
	s_waitcnt lgkmcnt(0)
	v_mfma_f32_32x32x16_bf16 v[112:127], v[80:83], v[180:183], v[112:127]
	v_mfma_f32_32x32x16_bf16 v[96:111], v[176:179], v[180:183], v[96:111]
	s_nop 15
	s_nop 3
	s_cbranch_vccnz .Lg1_b545
; __device__ __forceinline__ void mask_tile(f32x16& p0, f32x16& p1, int dq, unsigned W) {
;     const float NEG = -__builtin_inff();
; #pragma unroll
;     for (int r = 0; r < 16; ++r) {
;         const int c = (r & 3) + 8 * (r >> 2);
;         if ((unsigned)(dq - c) >= W) p0[r] = NEG;
;         if ((unsigned)(dq - c - 32) >= W) p1[r] = NEG;
;     }
	v_add_u32_e32 v172, 0x103b, v191
	v_cmp_gt_u32_e32 vcc, s33, v172
	v_add_u32_e32 v172, 27, v191
	s_nop 0
	v_cndmask_b32_e32 v112, v198, v112, vcc
	v_cmp_lt_u32_e32 vcc, s56, v172
	v_add_u32_e32 v172, 58, v191
	s_nop 0
	v_cndmask_b32_e32 v96, v198, v96, vcc
	v_cmp_lt_u32_e32 vcc, s56, v172
	v_add_u32_e32 v172, 26, v191
	s_nop 0
	v_cndmask_b32_e32 v113, v198, v113, vcc
	v_cmp_lt_u32_e32 vcc, s56, v172
	v_add_u32_e32 v172, 57, v191
	s_nop 0
	v_cndmask_b32_e32 v97, v198, v97, vcc
	v_cmp_lt_u32_e32 vcc, s56, v172
	v_add_u32_e32 v172, 25, v191
	s_nop 0
	v_cndmask_b32_e32 v114, v198, v114, vcc
	v_cmp_lt_u32_e32 vcc, s56, v172
	v_add_u32_e32 v172, 56, v191
	s_nop 0
	v_cndmask_b32_e32 v98, v198, v98, vcc
	v_cmp_lt_u32_e32 vcc, s56, v172
	v_add_u32_e32 v172, 24, v191
	s_nop 0
	v_cndmask_b32_e32 v115, v198, v115, vcc
	v_cmp_lt_u32_e32 vcc, s56, v172
	v_add_u32_e32 v172, 51, v191
	s_nop 0
	v_cndmask_b32_e32 v99, v198, v99, vcc
	v_cmp_lt_u32_e32 vcc, s56, v172
	v_add_u32_e32 v172, 19, v191
	s_nop 0
	v_cndmask_b32_e32 v116, v198, v116, vcc
	v_cmp_lt_u32_e32 vcc, s56, v172
	v_add_u32_e32 v172, 50, v191
	s_nop 0
	v_cndmask_b32_e32 v100, v198, v100, vcc
	v_cmp_lt_u32_e32 vcc, s56, v172
	v_add_u32_e32 v172, 18, v191
	s_nop 0
	v_cndmask_b32_e32 v117, v198, v117, vcc
	v_cmp_lt_u32_e32 vcc, s56, v172
	v_add_u32_e32 v172, 49, v191
	s_nop 0
	v_cndmask_b32_e32 v101, v198, v101, vcc
	v_cmp_lt_u32_e32 vcc, s56, v172
	v_add_u32_e32 v172, 17, v191
	s_nop 0
	v_cndmask_b32_e32 v118, v198, v118, vcc
	v_cmp_lt_u32_e32 vcc, s56, v172
	v_add_u32_e32 v172, 48, v191
	s_nop 0
	v_cndmask_b32_e32 v102, v198, v102, vcc
	v_cmp_lt_u32_e32 vcc, s56, v172
	v_add_u32_e32 v172, 16, v191
	s_nop 0
	v_cndmask_b32_e32 v119, v198, v119, vcc
	v_cmp_lt_u32_e32 vcc, s56, v172
	v_add_u32_e32 v172, 43, v191
	s_nop 0
	v_cndmask_b32_e32 v103, v198, v103, vcc
	v_cmp_lt_u32_e32 vcc, s56, v172
	v_add_u32_e32 v172, 11, v191
	s_nop 0
	v_cndmask_b32_e32 v120, v198, v120, vcc
	v_cmp_lt_u32_e32 vcc, s56, v172
	v_add_u32_e32 v172, 42, v191
	s_nop 0
	v_cndmask_b32_e32 v104, v198, v104, vcc
	v_cmp_lt_u32_e32 vcc, s56, v172
	v_add_u32_e32 v172, 10, v191
	s_nop 0
	v_cndmask_b32_e32 v121, v198, v121, vcc
	v_cmp_lt_u32_e32 vcc, s56, v172
	v_add_u32_e32 v172, 41, v191
	s_nop 0
	v_cndmask_b32_e32 v105, v198, v105, vcc
	v_cmp_lt_u32_e32 vcc, s56, v172
	v_add_u32_e32 v172, 9, v191
	s_nop 0
	v_cndmask_b32_e32 v122, v198, v122, vcc
	v_cmp_lt_u32_e32 vcc, s56, v172
	v_add_u32_e32 v172, 40, v191
	s_nop 0
	v_cndmask_b32_e32 v106, v198, v106, vcc
	v_cmp_lt_u32_e32 vcc, s56, v172
	v_add_u32_e32 v172, 8, v191
	s_nop 0
	v_cndmask_b32_e32 v123, v198, v123, vcc
	v_cmp_lt_u32_e32 vcc, s56, v172
	v_add_u32_e32 v172, 35, v191
	s_nop 0
	v_cndmask_b32_e32 v107, v198, v107, vcc
	v_cmp_lt_u32_e32 vcc, s56, v172
	v_add_u32_e32 v172, 3, v191
	s_nop 0
	v_cndmask_b32_e32 v124, v198, v124, vcc
	v_cmp_lt_u32_e32 vcc, s56, v172
	v_add_u32_e32 v172, 34, v191
	s_nop 0
	v_cndmask_b32_e32 v108, v198, v108, vcc
	v_cmp_lt_u32_e32 vcc, s56, v172
	v_add_u32_e32 v172, 2, v191
	s_nop 0
	v_cndmask_b32_e32 v125, v198, v125, vcc
	v_cmp_lt_u32_e32 vcc, s56, v172
	v_add_u32_e32 v172, 33, v191
	s_nop 0
	v_cndmask_b32_e32 v109, v198, v109, vcc
	v_cmp_lt_u32_e32 vcc, s56, v172
	v_add_u32_e32 v172, 1, v191
	s_nop 0
	v_cndmask_b32_e32 v126, v198, v126, vcc
	v_cmp_lt_u32_e32 vcc, s56, v172
	v_add_u32_e32 v172, 32, v191
	s_nop 0
	v_cndmask_b32_e32 v110, v198, v110, vcc
	v_cmp_lt_u32_e32 vcc, s56, v172
	s_nop 1
	v_cndmask_b32_e32 v127, v198, v127, vcc
	v_cmp_lt_u32_e32 vcc, s56, v191
	s_nop 1
	v_cndmask_b32_e32 v111, v198, v111, vcc
